# v22: HGRN pass A: 8 lo/hi bf16 store pairs -> ds_write_b32 via row_ror:8 exchange
# baseline (speedup 1.0000x reference)
; __device__ __forceinline__ float bf2f(unsigned short v) { return __uint_as_float(((unsigned)v) << 16); }
; __device__ __forceinline__ float sigmoidf_(float x) { return __builtin_amdgcn_rcpf(1.0f + __expf(-x)); }
; template <bool PA>
; __device__ __forceinline__ void hgrn_scan(unsigned char* lds, const bf16* Q, const bf16* FFb, const bf16* FBb, const bf16* Ib, bf16* OFb, bf16* OBb, const float* lbp, float* segm, int slab, int tid) {
;     ...
;             float bl[16], kvv[16], qv[16]; float run = 1.f;
; #pragma unroll
;             for (int jj = 0; jj < 16; ++jj) { const float f = bf2f(fraw[jj]); const float fg = lb + (1.0f - lb) * sigmoidf_(f); run *= fg; bl[jj] = run; kvv[jj] = 1.0f - fg; qv[jj] = bf2f(qraw[jj]); }
;             tot[seg * 128 + c] = run;
;             { const size_t row = cbase + (dir ? 63 - jr : jr);
;               const u32x4_t w0 = *(const u32x4_t*)(Ib + row * 1024 + head * 128 + part * 16), w1 = *(const u32x4_t*)(Ib + row * 1024 + head * 128 + part * 16 + 8);
;               const unsigned wa[8] = {w0.x, w0.y, w0.z, w0.w, w1.x, w1.y, w1.z, w1.w};
; #pragma unroll
;               for (int q = 0; q < 8; ++q) { iT[(part * 16 + 2 * q) * 72 + jr] = (bf16)(wa[q] & 0xffff); iT[(part * 16 + 2 * q + 1) * 72 + jr] = (bf16)(wa[q] >> 16); } }
.LBB0_68:
	s_waitcnt vmcnt(15)
	v_lshlrev_b32_e32 v0, 16, v156
	v_mul_f32_e32 v0, 0xbfb8aa3b, v0
	v_exp_f32_e32 v0, v0
	s_add_i32 s12, s24, 1
	s_and_b64 s[10:11], s[40:41], exec
	s_cselect_b32 s10, s49, s12
	v_lshl_add_u32 v204, s10, 6, v166
	v_ashrrev_i32_e32 v205, 31, v204
	v_lshlrev_b64 v[204:205], 11, v[204:205]
	v_lshl_add_u64 v[204:205], v[62:63], 0, v[204:205]
	global_load_dwordx4 v[208:211], v[204:205], off
	global_load_dwordx4 v[212:215], v[204:205], off offset:16
	v_add_f32_e32 v0, 1.0, v0
	v_rcp_f32_e32 v2, v0
	s_waitcnt vmcnt(16)
	v_lshlrev_b32_e32 v0, 16, v157
	v_mul_f32_e32 v0, 0xbfb8aa3b, v0
	v_exp_f32_e32 v0, v0
	s_add_i32 s49, s49, 1
	s_cmp_ge_i32 s49, s50
	v_add_f32_e32 v0, 1.0, v0
	v_rcp_f32_e32 v3, v0
	s_waitcnt vmcnt(15)
	v_lshlrev_b32_e32 v0, 16, v159
	v_mul_f32_e32 v0, 0xbfb8aa3b, v0
	v_exp_f32_e32 v0, v0
	v_pk_fma_f32 v[76:77], v[58:59], v[2:3], v[56:57]
	v_add_f32_e32 v0, 1.0, v0
	v_rcp_f32_e32 v4, v0
	s_waitcnt vmcnt(14)
	v_lshlrev_b32_e32 v0, 16, v160
	v_mul_f32_e32 v0, 0xbfb8aa3b, v0
	v_exp_f32_e32 v0, v0
	v_mul_f32_e32 v73, v76, v77
	v_add_f32_e32 v0, 1.0, v0
	v_rcp_f32_e32 v5, v0
	s_waitcnt vmcnt(13)
	v_lshlrev_b32_e32 v0, 16, v162
	v_mul_f32_e32 v0, 0xbfb8aa3b, v0
	v_exp_f32_e32 v0, v0
	v_pk_fma_f32 v[78:79], v[70:71], v[4:5], v[66:67]
	v_add_f32_e32 v0, 1.0, v0
	v_rcp_f32_e32 v2, v0
	s_waitcnt vmcnt(12)
	v_lshlrev_b32_e32 v0, 16, v163
	v_mul_f32_e32 v0, 0xbfb8aa3b, v0
	v_exp_f32_e32 v0, v0
	v_mul_f32_e32 v69, v73, v78
	v_mul_f32_e32 v61, v69, v79
	v_add_f32_e32 v0, 1.0, v0
	v_rcp_f32_e32 v3, v0
	s_waitcnt vmcnt(11)
	v_lshlrev_b32_e32 v0, 16, v164
	v_mul_f32_e32 v0, 0xbfb8aa3b, v0
	v_exp_f32_e32 v0, v0
	v_pk_fma_f32 v[82:83], v[58:59], v[2:3], v[56:57]
	v_add_f32_e32 v0, 1.0, v0
	v_rcp_f32_e32 v4, v0
	s_waitcnt vmcnt(10)
	v_lshlrev_b32_e32 v0, 16, v165
	v_mul_f32_e32 v0, 0xbfb8aa3b, v0
	v_exp_f32_e32 v0, v0
	v_mul_f32_e32 v65, v61, v82
	v_mul_f32_e32 v55, v65, v83
	v_add_f32_e32 v0, 1.0, v0
	v_rcp_f32_e32 v5, v0
	s_waitcnt vmcnt(9)
	v_lshlrev_b32_e32 v0, 16, v167
	v_mul_f32_e32 v0, 0xbfb8aa3b, v0
	v_exp_f32_e32 v0, v0
	v_pk_fma_f32 v[80:81], v[70:71], v[4:5], v[66:67]
	v_add_f32_e32 v0, 1.0, v0
	v_rcp_f32_e32 v2, v0
	s_waitcnt vmcnt(8)
	v_lshlrev_b32_e32 v0, 16, v168
	v_mul_f32_e32 v0, 0xbfb8aa3b, v0
	v_exp_f32_e32 v0, v0
	v_mul_f32_e32 v53, v55, v80
	v_mul_f32_e32 v51, v53, v81
	v_add_f32_e32 v0, 1.0, v0
	v_rcp_f32_e32 v3, v0
	s_waitcnt vmcnt(7)
	v_lshlrev_b32_e32 v0, 16, v169
	v_mul_f32_e32 v0, 0xbfb8aa3b, v0
	v_exp_f32_e32 v0, v0
	v_pk_fma_f32 v[86:87], v[58:59], v[2:3], v[56:57]
	v_add_f32_e32 v0, 1.0, v0
	v_rcp_f32_e32 v4, v0
	s_waitcnt vmcnt(6)
	v_lshlrev_b32_e32 v0, 16, v170
	v_mul_f32_e32 v0, 0xbfb8aa3b, v0
	v_exp_f32_e32 v0, v0
	v_mul_f32_e32 v49, v51, v86
	v_mul_f32_e32 v47, v49, v87
	v_add_f32_e32 v0, 1.0, v0
	v_rcp_f32_e32 v5, v0
	s_waitcnt vmcnt(5)
	v_lshlrev_b32_e32 v0, 16, v171
	v_mul_f32_e32 v0, 0xbfb8aa3b, v0
	v_exp_f32_e32 v0, v0
	v_pk_fma_f32 v[84:85], v[70:71], v[4:5], v[66:67]
	v_add_f32_e32 v0, 1.0, v0
	v_rcp_f32_e32 v2, v0
	s_waitcnt vmcnt(4)
	v_lshlrev_b32_e32 v0, 16, v172
	v_mul_f32_e32 v0, 0xbfb8aa3b, v0
	v_exp_f32_e32 v0, v0
	v_mul_f32_e32 v45, v47, v84
	v_mul_f32_e32 v43, v45, v85
	v_add_f32_e32 v0, 1.0, v0
	v_rcp_f32_e32 v3, v0
	s_waitcnt vmcnt(3)
	v_lshlrev_b32_e32 v0, 16, v173
	v_mul_f32_e32 v0, 0xbfb8aa3b, v0
	v_exp_f32_e32 v0, v0
	v_pk_fma_f32 v[90:91], v[58:59], v[2:3], v[56:57]
	v_lshl_add_u32 v2, s10, 6, v166
	v_ashrrev_i32_e32 v3, 31, v2
	v_add_f32_e32 v0, 1.0, v0
	v_rcp_f32_e32 v4, v0
	s_waitcnt vmcnt(2)
	v_lshlrev_b32_e32 v0, 16, v174
	v_mul_f32_e32 v0, 0xbfb8aa3b, v0
	v_exp_f32_e32 v0, v0
	v_lshlrev_b64 v[2:3], 11, v[2:3]
	v_lshl_add_u64 v[146:147], v[62:63], 0, v[2:3]
	v_mul_f32_e32 v41, v43, v90
	v_add_f32_e32 v0, 1.0, v0
	v_rcp_f32_e32 v5, v0
	v_mul_f32_e32 v39, v41, v91
	s_cselect_b64 s[10:11], -1, 0
	s_and_b64 vcc, exec, s[10:11]
	v_pk_fma_f32 v[88:89], v[70:71], v[4:5], v[66:67]
	s_nop 0
	v_mul_f32_e32 v37, v39, v88
	v_mul_f32_e32 v35, v37, v89
	ds_write_b32 v94, v35
	s_waitcnt vmcnt(1)
	v_bfe_u32 v217, v203, 3, 1
	v_sub_u32_e32 v216, 0, v217
	v_and_b32_e32 v216, 0x6060606, v216
	v_xor_b32_e32 v218, 0x5040100, v216
	v_mul_u32_u24_e32 v217, 0x8e, v217
	s_nop 1
	v_mov_b32_dpp v216, v208 row_ror:8 row_mask:0xf bank_mask:0xf
	v_add_u32_e32 v219, v217, v132
	v_perm_b32 v216, v216, v208, v218
	ds_write_b32 v219, v216 offset:62464
	s_nop 1
	v_mov_b32_dpp v216, v209 row_ror:8 row_mask:0xf bank_mask:0xf
	v_perm_b32 v216, v216, v209, v218
	ds_write_b32 v219, v216 offset:62752
	s_nop 1
	v_mov_b32_dpp v216, v210 row_ror:8 row_mask:0xf bank_mask:0xf
	v_perm_b32 v216, v216, v210, v218
	ds_write_b32 v219, v216 offset:63040
	s_nop 1
	v_mov_b32_dpp v216, v211 row_ror:8 row_mask:0xf bank_mask:0xf
	v_perm_b32 v216, v216, v211, v218
	ds_write_b32 v219, v216 offset:63328
	s_nop 0
	s_waitcnt vmcnt(0)
	s_nop 1
	v_mov_b32_dpp v216, v212 row_ror:8 row_mask:0xf bank_mask:0xf
	v_perm_b32 v216, v216, v212, v218
	ds_write_b32 v219, v216 offset:63616
	s_nop 1
	v_mov_b32_dpp v216, v213 row_ror:8 row_mask:0xf bank_mask:0xf
	v_perm_b32 v216, v216, v213, v218
	ds_write_b32 v219, v216 offset:63904
	s_nop 1
	v_mov_b32_dpp v216, v214 row_ror:8 row_mask:0xf bank_mask:0xf
	v_perm_b32 v216, v216, v214, v218
	ds_write_b32 v219, v216 offset:64192
	s_nop 1
	v_mov_b32_dpp v216, v215 row_ror:8 row_mask:0xf bank_mask:0xf
	v_perm_b32 v216, v216, v215, v218
	ds_write_b32 v219, v216 offset:64480
	s_cbranch_vccnz .LBB0_70
; template <bool PA>
; __device__ __forceinline__ void hgrn_scan(unsigned char* lds, const bf16* Q, const bf16* FFb, const bf16* FBb, const bf16* Ib, bf16* OFb, bf16* OBb, const float* lbp, float* segm, int slab, int tid) {
;     ...
;             if (p + 1 < p1) { const int nb = seqbase + (dir ? nch - 2 - p : p + 1) * 64;
; #pragma unroll
;                 for (int jj = 0; jj < 16; ++jj) { const int j = 16 * seg + jj; const unsigned bo = ((unsigned)(nb + (dir ? 63 - j : j)) * 1024u + (unsigned)hc) * 2u; qraw[jj] = PA ? (unsigned short)0 : *(const unsigned short*)((const char*)Q + bo); fraw[jj] = *(const unsigned short*)((const char*)Fp + bo); } }
	s_and_b64 s[12:13], s[40:41], exec
	s_cselect_b32 s12, s49, s24
	s_lshl_b32 s12, s12, 6
	s_add_i32 s12, s12, s51
	v_add_u32_e32 v0, s12, v17
	v_lshl_or_b32 v0, v0, 11, v140
	v_add_u32_e32 v2, s12, v141
	v_add_u32_e32 v3, s12, v142
	v_add_u32_e32 v4, s12, v143
	v_add_u32_e32 v5, s12, v144
	v_add_u32_e32 v75, s12, v145
	v_add_u32_e32 v146, s12, v148
	v_add_u32_e32 v147, s12, v149
	v_lshl_or_b32 v2, v2, 11, v140
	v_lshl_or_b32 v3, v3, 11, v140
	v_lshl_or_b32 v4, v4, 11, v140
	v_lshl_or_b32 v5, v5, 11, v140
	v_lshl_or_b32 v75, v75, 11, v140
	v_lshl_or_b32 v146, v146, 11, v140
	v_lshl_or_b32 v147, v147, 11, v140
	global_load_ushort v156, v0, s[8:9]
	global_load_ushort v157, v2, s[8:9]
	global_load_ushort v159, v3, s[8:9]
	global_load_ushort v160, v4, s[8:9]
	global_load_ushort v162, v5, s[8:9]
	global_load_ushort v163, v75, s[8:9]
	global_load_ushort v164, v146, s[8:9]
	global_load_ushort v165, v147, s[8:9]
	v_add_u32_e32 v0, s12, v150
	v_lshl_or_b32 v0, v0, 11, v140
	v_add_u32_e32 v2, s12, v151
	v_add_u32_e32 v3, s12, v152
	v_add_u32_e32 v4, s12, v153
	v_add_u32_e32 v5, s12, v154
	v_add_u32_e32 v75, s12, v155
	v_add_u32_e32 v146, s12, v158
	v_add_u32_e32 v147, s12, v161
	v_lshl_or_b32 v2, v2, 11, v140
	v_lshl_or_b32 v3, v3, 11, v140
	v_lshl_or_b32 v4, v4, 11, v140
	v_lshl_or_b32 v5, v5, 11, v140
	v_lshl_or_b32 v75, v75, 11, v140
	v_lshl_or_b32 v146, v146, 11, v140
	v_lshl_or_b32 v147, v147, 11, v140
	global_load_ushort v167, v0, s[8:9]
	global_load_ushort v168, v2, s[8:9]
	global_load_ushort v169, v3, s[8:9]
	global_load_ushort v170, v4, s[8:9]
	global_load_ushort v171, v5, s[8:9]
	global_load_ushort v172, v75, s[8:9]
	global_load_ushort v173, v146, s[8:9]
	global_load_ushort v174, v147, s[8:9]
